# plus M3 merge: per-row-panel K-rotation of staged K-tiles (stagger, mult 5)
# baseline (speedup 1.0000x reference)
.LBB0_1007:
	s_or_b64 exec, exec, s[2:3]
	v_readlane_b32 s0, v253, 5
	s_waitcnt lgkmcnt(0)
	s_barrier
	v_mov_b32_e32 v1, s0
	ds_read_b32 v1, v1
	v_readlane_b32 s0, v253, 30
	v_readlane_b32 s1, v253, 31
	s_mov_b32 s1, s89
	s_mul_i32 s48, s0, 0x1f80
	s_waitcnt lgkmcnt(0)
	v_cmp_lt_i32_e32 vcc, s64, v1
	s_mov_b64 s[94:95], s[0:1]
	s_lshl_b64 s[68:69], s[0:1], 12
	v_readfirstlane_b32 s36, v1
	s_mov_b32 s51, 0
	s_barrier
	s_cbranch_vccnz .LBB0_1083
	s_lshl_b32 s18, s39, 4
	v_readlane_b32 s52, v251, 16
	v_writelane_b32 v254, s4, 15
	s_and_b32 s50, s18, 0xfffffc00
	s_ashr_i32 s18, s36, 3
	v_readlane_b32 s56, v251, 20
	v_readlane_b32 s57, v251, 21
	v_writelane_b32 v254, s5, 16
	s_ashr_i32 s19, s18, 31
	v_readlane_b32 s58, v251, 22
	v_readlane_b32 s59, v251, 23
	v_readlane_b32 s60, v251, 24
	v_readlane_b32 s61, v251, 25
	v_readlane_b32 s62, v251, 26
	v_readlane_b32 s63, v251, 27
	v_readlane_b32 s64, v251, 28
	v_readlane_b32 s65, v251, 29
	v_readlane_b32 s66, v251, 30
	v_readlane_b32 s67, v251, 31
	s_mov_b64 s[4:5], s[56:57]
	s_ashr_i32 s49, s39, 7
	s_and_b32 s22, s39, 64
	s_lshl_b64 s[18:19], s[18:19], 19
	s_mov_b64 s[14:15], s[66:67]
	s_add_u32 s18, s14, s18
	s_addc_u32 s19, s15, s19
	s_lshl_b32 s20, s36, 7
	s_and_b32 s20, s20, 0x380
	s_addk_i32 s20, 0xf80
	s_add_u32 s20, s48, s20
	s_addc_u32 s21, 0, 0
	s_mov_b64 s[8:9], s[60:61]
	s_lshl_b64 s[20:21], s[20:21], 11
	s_add_u32 s20, s8, s20
	s_addc_u32 s21, s9, s21
	s_and_b32 s23, s36, 0x7fffff8
	v_and_b32_e32 v1, 15, v2
	s_mov_b64 s[6:7], s[58:59]
	s_mov_b64 s[10:11], s[62:63]
	s_mov_b64 s[12:13], s[64:65]
	s_add_i32 s23, s23, s49
	s_waitcnt vmcnt(4)
	v_lshl_or_b32 v4, s23, 5, v1
	v_readlane_b32 s0, v253, 32
	v_ashrrev_i32_e32 v5, 31, v4
	v_readlane_b32 s1, v253, 33
	v_lshrrev_b32_e32 v3, 4, v2
	s_and_b32 s23, s39, 0xffffff80
	v_lshl_add_u64 v[4:5], v[4:5], 2, s[0:1]
	global_load_dword v18, v[4:5], off
	global_load_dword v19, v[4:5], off offset:64
	global_load_dword v20, v[4:5], off offset:512
	global_load_dword v21, v[4:5], off offset:576
	v_mov_b32_e32 v5, 0x2000
	v_ashrrev_i32_e32 v4, 3, v2
	v_lshl_add_u32 v5, v2, 4, v5
	v_bfe_u32 v50, v2, 4, 2
	v_lshrrev_b32_e32 v6, 1, v2
	v_bfe_u32 v7, v2, 1, 3
	v_xor_b32_e32 v2, v3, v2
	s_add_i32 s23, s23, 0
	v_lshlrev_b32_e32 v2, 4, v2
	s_waitcnt vmcnt(4)
	v_lshl_add_u32 v22, v1, 2, s23
	v_and_b32_e32 v2, 0x70, v2
	s_add_i32 s26, s50, 0
	v_add_u32_e32 v177, 0x24000, v22
	v_lshl_or_b32 v166, v4, 11, v2
	s_mov_b32 m0, s26
	v_ashrrev_i32_e32 v3, 7, v5
	v_lshl_or_b32 v168, v3, 11, v2
	v_mov_b32_e32 v167, v0
	v_lshl_or_b32 v171, s49, 5, v1
	v_bitop3_b32 v5, v6, v50, 7 bitop3:0x6c
	v_bitop3_b32 v6, v50, v7, 4 bitop3:0x36
	v_or_b32_e32 v7, s22, v1
	v_lshlrev_b32_e32 v5, 4, v5
	v_lshlrev_b32_e32 v6, 4, v6
	v_lshlrev_b32_e32 v8, 7, v171
	v_lshlrev_b32_e32 v7, 7, v7
	v_lshl_or_b32 v170, v4, 9, v2
	v_lshl_or_b32 v172, v3, 9, v2
	v_lshl_add_u64 v[2:3], s[18:19], 0, v[166:167]
	s_mov_b64 s[0:1], 0x80
	v_mov_b32_e32 v169, v0
	v_or_b32_e32 v174, v6, v8
	v_or_b32_e32 v175, v5, v7
	v_or_b32_e32 v176, v6, v7
	v_lshl_add_u64 v[6:7], v[2:3], 0, s[0:1]
	v_or_b32_e32 v173, v8, v5
	v_lshl_add_u64 v[4:5], s[18:19], 0, v[168:169]
	v_lshl_add_u64 v[8:9], v[4:5], 0, s[0:1]
	v_lshl_add_u64 v[10:11], s[20:21], 0, v[166:167]
	v_lshl_add_u64 v[12:13], s[20:21], 0, v[168:169]
	v_lshl_add_u64 v[14:15], v[10:11], 0, s[0:1]
	v_lshl_add_u64 v[16:17], v[12:13], 0, s[0:1]
	s_mov_b64 s[0:1], 0x100
	v_lshl_add_u64 v[2:3], v[2:3], 0, s[0:1]
	v_add_u32_e32 v38, 0, v175
	v_add_u32_e32 v46, 0, v176
	v_readlane_b32 s53, v251, 17
	v_readlane_b32 s54, v251, 18
	s_waitcnt vmcnt(2)
	ds_write2_b32 v177, v18, v19 offset1:16
	s_waitcnt vmcnt(0)
	ds_write2_b32 v177, v20, v21 offset0:128 offset1:144
	global_load_lds_dwordx4 v166, s[18:19]
	s_add_i32 m0, s26, 0x2000
	s_add_u32 s24, s18, 0x40000
	global_load_lds_dwordx4 v168, s[18:19]
	s_addc_u32 s25, s19, 0
	s_add_i32 m0, s26, 0x4000
	v_readlane_b32 s55, v251, 19
	global_load_lds_dwordx4 v166, s[24:25]
	s_add_i32 m0, s26, 0x6000
	v_mov_b32_e32 v82, 0
	global_load_lds_dwordx4 v168, s[24:25]
	s_add_i32 m0, s26, 0x8000
	s_movk_i32 s64, 0x3ff
	global_load_lds_dwordx4 v166, s[20:21]
	s_add_i32 m0, s26, 0xa000
	s_mov_b32 s38, 3
	global_load_lds_dwordx4 v168, s[20:21]
	s_add_i32 m0, s26, 0xc000
	s_mov_b32 s51, 1
	global_load_lds_dwordx4 v[6:7], off
	s_add_i32 m0, s26, 0xe000
	s_add_u32 s24, s18, 0x40080
	global_load_lds_dwordx4 v[8:9], off
	s_addc_u32 s25, s19, 0
	s_add_i32 m0, s26, 0x10000
	v_add_u32_e32 v6, 0, v173
	global_load_lds_dwordx4 v166, s[24:25]
	s_add_i32 m0, s26, 0x12000
	v_lshl_or_b32 v178, v50, 3, s22
	global_load_lds_dwordx4 v168, s[24:25]
	s_add_i32 m0, s26, 0x14000
	s_mov_b64 s[22:23], 0
	global_load_lds_dwordx4 v[14:15], off
	s_add_i32 m0, s26, 0x16000
	v_add_u32_e32 v14, 0, v174
	global_load_lds_dwordx4 v[16:17], off
	s_add_i32 m0, s26, 0x18000
	s_mov_b32 s57, 16
	global_load_lds_dwordx4 v[2:3], off
	s_add_i32 m0, s26, 0x1a000
	v_lshl_add_u64 v[2:3], v[4:5], 0, s[0:1]
	s_add_u32 s24, s18, 0x40100
	global_load_lds_dwordx4 v[2:3], off
	s_addc_u32 s25, s19, 0
	s_add_i32 m0, s26, 0x1c000
	v_lshl_add_u64 v[2:3], v[10:11], 0, s[0:1]
	global_load_lds_dwordx4 v166, s[24:25]
	s_add_i32 m0, s26, 0x1e000
	s_mov_b32 s37, 0
	global_load_lds_dwordx4 v168, s[24:25]
	s_add_i32 m0, s26, 0x20000
	v_mov_b32_e32 v179, 0
	global_load_lds_dwordx4 v[2:3], off
	v_lshl_add_u64 v[2:3], v[12:13], 0, s[0:1]
	s_add_i32 m0, s26, 0x22000
	s_add_u32 s18, s18, 0x180
	global_load_lds_dwordx4 v[2:3], off
	s_waitcnt vmcnt(12)
	s_barrier
	ds_read_b128 v[2:5], v6
	ds_read_b128 v[6:9], v6 offset:2048
	ds_read_b128 v[10:13], v14
	ds_read_b128 v[14:17], v14 offset:2048
	ds_read_b128 v[18:21], v38 offset:32768
	ds_read_b128 v[22:25], v38 offset:34816
	ds_read_b128 v[26:29], v46 offset:32768
	ds_read_b128 v[30:33], v46 offset:34816
	ds_read_b128 v[34:37], v38 offset:36864
	ds_read_b128 v[38:41], v38 offset:38912
	ds_read_b128 v[42:45], v46 offset:36864
	ds_read_b128 v[46:49], v46 offset:38912
	s_addc_u32 s19, s19, 0
	s_add_u32 s20, s20, 0x180
	s_addc_u32 s21, s21, 0
	s_mov_b64 s[26:27], -1
	v_mov_b32_e32 v180, 0
	v_mov_b32_e32 v181, 0
	v_mov_b32_e32 v197, 0
	v_mov_b32_e32 v198, 0
	v_mov_b32_e32 v199, 0
	v_mov_b32_e32 v200, 0
	v_mov_b32_e32 v201, 0
	v_mov_b32_e32 v202, 0
	v_mov_b32_e32 v203, 0
	v_mov_b32_e32 v204, 0
	v_mov_b32_e32 v205, 0
	v_mov_b32_e32 v206, 0
	v_mov_b32_e32 v207, 0
	v_mov_b32_e32 v208, 0
	v_mov_b32_e32 v209, 0
	v_mov_b32_e32 v210, 0
	v_mov_b32_e32 v211, 0
	v_mov_b32_e32 v212, 0
	v_mov_b32_e32 v213, 0
	v_mov_b32_e32 v214, 0
	v_mov_b32_e32 v215, 0
	v_mov_b32_e32 v216, 0
	v_mov_b32_e32 v217, 0
	v_mov_b32_e32 v218, 0
	v_mov_b32_e32 v219, 0
	v_mov_b32_e32 v220, 0
	v_mov_b32_e32 v221, 0
	v_mov_b32_e32 v222, 0
	v_mov_b32_e32 v223, 0
	v_mov_b32_e32 v224, 0
	v_mov_b32_e32 v225, 0
	v_mov_b32_e32 v56, 0
	v_mov_b32_e32 v57, 0
	v_mov_b32_e32 v54, 0
	v_mov_b32_e32 v55, 0
	v_mov_b32_e32 v60, 0
	v_mov_b32_e32 v61, 0
	v_mov_b32_e32 v58, 0
	v_mov_b32_e32 v59, 0
	v_mov_b32_e32 v64, 0
	v_mov_b32_e32 v65, 0
	v_mov_b32_e32 v62, 0
	v_mov_b32_e32 v63, 0
	v_mov_b32_e32 v68, 0
	v_mov_b32_e32 v69, 0
	v_mov_b32_e32 v66, 0
	v_mov_b32_e32 v67, 0
	v_mov_b32_e32 v72, 0
	v_mov_b32_e32 v73, 0
	v_mov_b32_e32 v70, 0
	v_mov_b32_e32 v71, 0
	v_mov_b32_e32 v76, 0
	v_mov_b32_e32 v77, 0
	v_mov_b32_e32 v74, 0
	v_mov_b32_e32 v75, 0
	v_mov_b32_e32 v80, 0
	v_mov_b32_e32 v81, 0
	v_mov_b32_e32 v78, 0
	v_mov_b32_e32 v79, 0
	v_mov_b32_e32 v52, 0
	v_mov_b32_e32 v53, 0
	v_mov_b32_e32 v50, 0
	v_mov_b32_e32 v51, 0
	s_mov_b32 s61, 3
	s_mov_b32 s59, 0
	s_mov_b32 s60, 0
	s_mov_b32 s58, 0
	s_mov_b64 s[30:31], 0
	s_mov_b32 s52, 0
	s_mov_b64 s[24:25], 0
	s_mov_b32 s56, 16
	s_mov_b32 s53, 0
	s_mov_b32 s55, 0
	s_mov_b32 s54, s36
	v_mov_b32_e32 v83, v82
	v_mov_b32_e32 v84, v82
	v_mov_b32_e32 v85, v82
	v_mov_b32_e32 v86, v82
	v_mov_b32_e32 v87, v82
	v_mov_b32_e32 v88, v82
	v_mov_b32_e32 v89, v82
	v_mov_b32_e32 v90, v82
	v_mov_b32_e32 v91, v82
	v_mov_b32_e32 v92, v82
	v_mov_b32_e32 v93, v82
	v_mov_b32_e32 v94, v82
	v_mov_b32_e32 v95, v82
	v_mov_b32_e32 v96, v82
	v_mov_b32_e32 v97, v82
	v_mov_b32_e32 v98, v82
	v_mov_b32_e32 v99, v82
	v_mov_b32_e32 v100, v82
	v_mov_b32_e32 v101, v82
	v_mov_b32_e32 v102, v82
	v_mov_b32_e32 v103, v82
	v_mov_b32_e32 v104, v82
	v_mov_b32_e32 v105, v82
	v_mov_b32_e32 v106, v82
	v_mov_b32_e32 v107, v82
	v_mov_b32_e32 v108, v82
	v_mov_b32_e32 v109, v82
	v_mov_b32_e32 v110, v82
	v_mov_b32_e32 v111, v82
	v_mov_b32_e32 v112, v82
	v_mov_b32_e32 v113, v82
	v_mov_b32_e32 v114, v82
	v_mov_b32_e32 v115, v82
	v_mov_b32_e32 v116, v82
	v_mov_b32_e32 v117, v82
	v_mov_b32_e32 v118, v82
	v_mov_b32_e32 v119, v82
	v_mov_b32_e32 v120, v82
	v_mov_b32_e32 v121, v82
	v_mov_b32_e32 v122, v82
	v_mov_b32_e32 v123, v82
	v_mov_b32_e32 v124, v82
	v_mov_b32_e32 v125, v82
	v_mov_b32_e32 v126, v82
	v_mov_b32_e32 v127, v82
	v_mov_b32_e32 v128, v82
	v_mov_b32_e32 v129, v82
	v_mov_b32_e32 v130, v82
	v_mov_b32_e32 v131, v82
	v_mov_b32_e32 v132, v82
	v_mov_b32_e32 v133, v82
	v_mov_b32_e32 v134, v82
	v_mov_b32_e32 v135, v82
	v_mov_b32_e32 v136, v82
	v_mov_b32_e32 v137, v82
	v_mov_b32_e32 v138, v82
	v_mov_b32_e32 v139, v82
	v_mov_b32_e32 v140, v82
	v_mov_b32_e32 v141, v82
	v_mov_b32_e32 v142, v82
	v_mov_b32_e32 v143, v82
	v_mov_b32_e32 v144, v82
	v_mov_b32_e32 v145, v82
	v_readlane_b32 s2, v253, 34
	v_readlane_b32 s3, v253, 35
	v_readlane_b32 s4, v253, 36
	v_readlane_b32 s5, v253, 37
	v_readlane_b32 s6, v253, 38
	v_readlane_b32 s7, v253, 39
	v_readlane_b32 s8, v253, 40
	v_readlane_b32 s9, v253, 41
	v_readlane_b32 s10, v253, 42
	v_readlane_b32 s11, v253, 43
	v_readlane_b32 s12, v253, 44
	v_readlane_b32 s13, v253, 45
	v_readlane_b32 s14, v253, 46
	v_readlane_b32 s15, v253, 47
	s_mov_b32 s98, 0x7fffffff
	s_mov_b32 s99, 0

.LBB0_1013:
	s_waitcnt lgkmcnt(0)
	s_andn2_b64 vcc, exec, s[26:27]
	s_barrier
	s_cbranch_vccnz .LBB0_1063
	s_add_i32 s28, s34, s50
	v_lshl_add_u64 v[226:227], s[18:19], 0, v[166:167]
	s_mov_b32 m0, s28
	v_cndmask_b32_e64 v228, v168, v172, s[22:23]
	global_load_lds_dwordx4 v[226:227], off
	s_add_i32 m0, s28, 0x2000
	s_add_u32 s26, s18, 0x40000
	v_lshl_add_u64 v[226:227], s[18:19], 0, v[168:169]
	s_addc_u32 s27, s19, 0
	global_load_lds_dwordx4 v[226:227], off
	v_lshl_add_u64 v[226:227], s[26:27], 0, v[166:167]
	s_add_i32 m0, s28, 0x4000
	v_mov_b32_e32 v229, v0
	global_load_lds_dwordx4 v[226:227], off
	v_lshl_add_u64 v[226:227], s[26:27], 0, v[168:169]
	s_add_i32 m0, s28, 0x6000
	s_add_i32 s38, s38, 1
	global_load_lds_dwordx4 v[226:227], off
	v_cndmask_b32_e64 v226, v166, v170, s[22:23]
	v_mov_b32_e32 v227, v0
	s_add_i32 m0, s28, 0x8000
	v_lshl_add_u64 v[226:227], s[20:21], 0, v[226:227]
	global_load_lds_dwordx4 v[226:227], off
	v_lshl_add_u64 v[226:227], s[20:21], 0, v[228:229]
	s_add_i32 m0, s28, 0xa000
	s_add_u32 s18, s18, 0x80
	global_load_lds_dwordx4 v[226:227], off
	s_addc_u32 s19, s19, 0
	s_add_u32 s20, s20, 0x80
	s_addc_u32 s21, s21, 0
	s_cmp_lg_u32 s38, s98
	s_cbranch_scc1 .Lrot_nowrap
	s_sub_u32 s18, s18, s99
	s_subb_u32 s19, s19, 0
	s_sub_u32 s20, s20, s99
	s_subb_u32 s21, s21, 0
.Lrot_nowrap:
	s_cmp_lg_u32 s38, s57
	s_mov_b64 s[26:27], -1
	s_cbranch_scc1 .LBB0_1062
	s_add_i32 s37, s37, 1
	s_cmp_lg_u32 s37, 6
	s_mov_b64 s[28:29], -1
	s_cbranch_scc1 .LBB0_1051
	v_readlane_b32 s0, v253, 26
	v_readlane_b32 s1, v253, 27
	s_and_saveexec_b64 s[26:27], s[0:1]
	s_cbranch_execz .LBB0_1048
	s_mov_b64 s[30:31], exec
	v_mbcnt_lo_u32_b32 v186, s30, 0
	v_mbcnt_hi_u32_b32 v195, s31, v186
	v_cmp_eq_u32_e32 vcc, 0, v195
	s_and_saveexec_b64 s[28:29], vcc
	s_cbranch_execz .LBB0_1019
	s_bcnt1_i32_b64 s30, s[30:31]
	v_mov_b32_e32 v186, s30
	global_atomic_add v226, v0, v186, s[16:17] sc0

.LBB0_1060:
	s_lshr_b32 s98, s36, 3
	s_mul_i32 s98, s98, 5
	s_add_i32 s99, s58, -1
	s_and_b32 s98, s98, s99
	s_lshl_b32 s99, s98, 7
	s_add_u32 s18, s18, s99
	s_addc_u32 s19, s19, 0
	s_add_u32 s20, s20, s99
	s_addc_u32 s21, s21, 0
	s_sub_i32 s98, s58, s98
	s_lshl_b32 s99, s58, 7
	s_mov_b32 s57, 0
	s_mov_b64 s[26:27], -1
	s_mov_b32 s60, s37
	s_mov_b32 s59, s36
	s_mov_b32 s28, s58
